# P3 LRU job prologue: gate-weight staging as a counted-wait pipeline (3 slices in flight) instead of 3 batches with vmcnt(0), and the per-channel parameter loads hoisted ahead of it
# baseline (speedup 1.0000x reference)
.LBB0_578:
	s_lshl_b32 s12, s29, 7
	v_add_u32_e32 v96, s12, v186
	v_ashrrev_i32_e32 v97, 31, v96
	v_lshlrev_b64 v[148:149], 2, v[96:97]
	v_readlane_b32 s30, v254, 14
	v_readlane_b32 s31, v254, 15
	v_readlane_b32 s32, v254, 38
	v_readlane_b32 s33, v254, 39
	v_readlane_b32 s34, v254, 36
	v_readlane_b32 s35, v254, 37
	s_nop 1
	v_lshl_add_u64 v[150:151], s[32:33], 0, v[148:149]
	global_load_dword v3, v[150:151], off
	v_lshl_add_u64 v[150:151], s[30:31], 0, v[148:149]
	global_load_dword v0, v[150:151], off
	v_lshl_add_u64 v[150:151], s[34:35], 0, v[148:149]
	global_load_dword v1, v[150:151], off
	v_mov_b32_e32 v152, v188
	v_lshlrev_b64 v[8:9], 2, v[152:153]
	v_lshl_add_u64 v[10:11], s[6:7], 0, v[8:9]
	v_lshl_add_u64 v[12:13], s[44:45], 0, v[8:9]
	global_load_dword v16, v[10:11], off
	global_load_dword v17, v[10:11], off offset:512
	global_load_dword v18, v[10:11], off offset:1024
	global_load_dword v19, v[10:11], off offset:1536
	global_load_dword v20, v[10:11], off offset:2048
	global_load_dword v21, v[10:11], off offset:2560
	global_load_dword v22, v[10:11], off offset:3072
	global_load_dword v23, v[10:11], off offset:3584
	global_load_dword v24, v[12:13], off
	global_load_dword v25, v[12:13], off offset:512
	global_load_dword v26, v[12:13], off offset:1024
	global_load_dword v27, v[12:13], off offset:1536
	global_load_dword v28, v[12:13], off offset:2048
	global_load_dword v29, v[12:13], off offset:2560
	global_load_dword v30, v[12:13], off offset:3072
	global_load_dword v31, v[12:13], off offset:3584
	v_add_u32_e32 v152, 0x800, v188
	v_lshlrev_b64 v[8:9], 2, v[152:153]
	v_lshl_add_u64 v[10:11], s[6:7], 0, v[8:9]
	v_lshl_add_u64 v[12:13], s[44:45], 0, v[8:9]
	global_load_dword v32, v[10:11], off
	global_load_dword v33, v[10:11], off offset:512
	global_load_dword v34, v[10:11], off offset:1024
	global_load_dword v35, v[10:11], off offset:1536
	global_load_dword v36, v[10:11], off offset:2048
	global_load_dword v37, v[10:11], off offset:2560
	global_load_dword v38, v[10:11], off offset:3072
	global_load_dword v39, v[10:11], off offset:3584
	global_load_dword v40, v[12:13], off
	global_load_dword v41, v[12:13], off offset:512
	global_load_dword v42, v[12:13], off offset:1024
	global_load_dword v43, v[12:13], off offset:1536
	global_load_dword v44, v[12:13], off offset:2048
	global_load_dword v45, v[12:13], off offset:2560
	global_load_dword v46, v[12:13], off offset:3072
	global_load_dword v47, v[12:13], off offset:3584
	v_add_u32_e32 v152, 0x1000, v188
	v_lshlrev_b64 v[8:9], 2, v[152:153]
	v_lshl_add_u64 v[10:11], s[6:7], 0, v[8:9]
	v_lshl_add_u64 v[12:13], s[44:45], 0, v[8:9]
	global_load_dword v48, v[10:11], off
	global_load_dword v49, v[10:11], off offset:512
	global_load_dword v50, v[10:11], off offset:1024
	global_load_dword v51, v[10:11], off offset:1536
	global_load_dword v52, v[10:11], off offset:2048
	global_load_dword v53, v[10:11], off offset:2560
	global_load_dword v54, v[10:11], off offset:3072
	global_load_dword v55, v[10:11], off offset:3584
	global_load_dword v56, v[12:13], off
	global_load_dword v57, v[12:13], off offset:512
	global_load_dword v58, v[12:13], off offset:1024
	global_load_dword v59, v[12:13], off offset:1536
	global_load_dword v60, v[12:13], off offset:2048
	global_load_dword v61, v[12:13], off offset:2560
	global_load_dword v62, v[12:13], off offset:3072
	global_load_dword v63, v[12:13], off offset:3584
	s_waitcnt vmcnt(32)
	v_cvt_pk_bf16_f32 v4, v16, v17
	v_cvt_pk_bf16_f32 v5, v18, v19
	v_cvt_pk_bf16_f32 v6, v20, v21
	v_cvt_pk_bf16_f32 v7, v22, v23
	ds_write_b128 v2, v[4:7]
	v_cvt_pk_bf16_f32 v144, v24, v25
	v_cvt_pk_bf16_f32 v145, v26, v27
	v_cvt_pk_bf16_f32 v146, v28, v29
	v_cvt_pk_bf16_f32 v147, v30, v31
	ds_write_b128 v2, v[144:147] offset:8192
	v_add_u32_e32 v152, 0x1800, v188
	v_lshlrev_b64 v[8:9], 2, v[152:153]
	v_lshl_add_u64 v[10:11], s[6:7], 0, v[8:9]
	v_lshl_add_u64 v[12:13], s[44:45], 0, v[8:9]
	global_load_dword v64, v[10:11], off
	global_load_dword v65, v[10:11], off offset:512
	global_load_dword v66, v[10:11], off offset:1024
	global_load_dword v67, v[10:11], off offset:1536
	global_load_dword v68, v[10:11], off offset:2048
	global_load_dword v69, v[10:11], off offset:2560
	global_load_dword v70, v[10:11], off offset:3072
	global_load_dword v71, v[10:11], off offset:3584
	global_load_dword v72, v[12:13], off
	global_load_dword v73, v[12:13], off offset:512
	global_load_dword v74, v[12:13], off offset:1024
	global_load_dword v75, v[12:13], off offset:1536
	global_load_dword v76, v[12:13], off offset:2048
	global_load_dword v77, v[12:13], off offset:2560
	global_load_dword v78, v[12:13], off offset:3072
	global_load_dword v79, v[12:13], off offset:3584
	s_waitcnt vmcnt(32)
	v_cvt_pk_bf16_f32 v4, v32, v33
	v_cvt_pk_bf16_f32 v5, v34, v35
	v_cvt_pk_bf16_f32 v6, v36, v37
	v_cvt_pk_bf16_f32 v7, v38, v39
	ds_write_b128 v2, v[4:7] offset:1024
	v_cvt_pk_bf16_f32 v144, v40, v41
	v_cvt_pk_bf16_f32 v145, v42, v43
	v_cvt_pk_bf16_f32 v146, v44, v45
	v_cvt_pk_bf16_f32 v147, v46, v47
	ds_write_b128 v2, v[144:147] offset:9216
	v_add_u32_e32 v152, 0x2000, v188
	v_lshlrev_b64 v[8:9], 2, v[152:153]
	v_lshl_add_u64 v[10:11], s[6:7], 0, v[8:9]
	v_lshl_add_u64 v[12:13], s[44:45], 0, v[8:9]
	global_load_dword v80, v[10:11], off
	global_load_dword v81, v[10:11], off offset:512
	global_load_dword v82, v[10:11], off offset:1024
	global_load_dword v83, v[10:11], off offset:1536
	global_load_dword v84, v[10:11], off offset:2048
	global_load_dword v85, v[10:11], off offset:2560
	global_load_dword v86, v[10:11], off offset:3072
	global_load_dword v87, v[10:11], off offset:3584
	global_load_dword v88, v[12:13], off
	global_load_dword v89, v[12:13], off offset:512
	global_load_dword v90, v[12:13], off offset:1024
	global_load_dword v91, v[12:13], off offset:1536
	global_load_dword v92, v[12:13], off offset:2048
	global_load_dword v93, v[12:13], off offset:2560
	global_load_dword v94, v[12:13], off offset:3072
	global_load_dword v95, v[12:13], off offset:3584
	s_waitcnt vmcnt(32)
	v_cvt_pk_bf16_f32 v4, v48, v49
	v_cvt_pk_bf16_f32 v5, v50, v51
	v_cvt_pk_bf16_f32 v6, v52, v53
	v_cvt_pk_bf16_f32 v7, v54, v55
	ds_write_b128 v2, v[4:7] offset:2048
	v_cvt_pk_bf16_f32 v144, v56, v57
	v_cvt_pk_bf16_f32 v145, v58, v59
	v_cvt_pk_bf16_f32 v146, v60, v61
	v_cvt_pk_bf16_f32 v147, v62, v63
	ds_write_b128 v2, v[144:147] offset:10240
	v_add_u32_e32 v152, 0x2800, v188
	v_lshlrev_b64 v[8:9], 2, v[152:153]
	v_lshl_add_u64 v[10:11], s[6:7], 0, v[8:9]
	v_lshl_add_u64 v[12:13], s[44:45], 0, v[8:9]
	global_load_dword v96, v[10:11], off
	global_load_dword v97, v[10:11], off offset:512
	global_load_dword v98, v[10:11], off offset:1024
	global_load_dword v99, v[10:11], off offset:1536
	global_load_dword v100, v[10:11], off offset:2048
	global_load_dword v101, v[10:11], off offset:2560
	global_load_dword v102, v[10:11], off offset:3072
	global_load_dword v103, v[10:11], off offset:3584
	global_load_dword v104, v[12:13], off
	global_load_dword v105, v[12:13], off offset:512
	global_load_dword v106, v[12:13], off offset:1024
	global_load_dword v107, v[12:13], off offset:1536
	global_load_dword v108, v[12:13], off offset:2048
	global_load_dword v109, v[12:13], off offset:2560
	global_load_dword v110, v[12:13], off offset:3072
	global_load_dword v111, v[12:13], off offset:3584
	s_waitcnt vmcnt(32)
	v_cvt_pk_bf16_f32 v4, v64, v65
	v_cvt_pk_bf16_f32 v5, v66, v67
	v_cvt_pk_bf16_f32 v6, v68, v69
	v_cvt_pk_bf16_f32 v7, v70, v71
	ds_write_b128 v2, v[4:7] offset:3072
	v_cvt_pk_bf16_f32 v144, v72, v73
	v_cvt_pk_bf16_f32 v145, v74, v75
	v_cvt_pk_bf16_f32 v146, v76, v77
	v_cvt_pk_bf16_f32 v147, v78, v79
	ds_write_b128 v2, v[144:147] offset:11264
	v_add_u32_e32 v152, 0x3000, v188
	v_lshlrev_b64 v[8:9], 2, v[152:153]
	v_lshl_add_u64 v[10:11], s[6:7], 0, v[8:9]
	v_lshl_add_u64 v[12:13], s[44:45], 0, v[8:9]
	global_load_dword v112, v[10:11], off
	global_load_dword v113, v[10:11], off offset:512
	global_load_dword v114, v[10:11], off offset:1024
	global_load_dword v115, v[10:11], off offset:1536
	global_load_dword v116, v[10:11], off offset:2048
	global_load_dword v117, v[10:11], off offset:2560
	global_load_dword v118, v[10:11], off offset:3072
	global_load_dword v119, v[10:11], off offset:3584
	global_load_dword v120, v[12:13], off
	global_load_dword v121, v[12:13], off offset:512
	global_load_dword v122, v[12:13], off offset:1024
	global_load_dword v123, v[12:13], off offset:1536
	global_load_dword v124, v[12:13], off offset:2048
	global_load_dword v125, v[12:13], off offset:2560
	global_load_dword v126, v[12:13], off offset:3072
	global_load_dword v127, v[12:13], off offset:3584
	s_waitcnt vmcnt(32)
	v_cvt_pk_bf16_f32 v4, v80, v81
	v_cvt_pk_bf16_f32 v5, v82, v83
	v_cvt_pk_bf16_f32 v6, v84, v85
	v_cvt_pk_bf16_f32 v7, v86, v87
	ds_write_b128 v2, v[4:7] offset:4096
	v_cvt_pk_bf16_f32 v144, v88, v89
	v_cvt_pk_bf16_f32 v145, v90, v91
	v_cvt_pk_bf16_f32 v146, v92, v93
	v_cvt_pk_bf16_f32 v147, v94, v95
	ds_write_b128 v2, v[144:147] offset:12288
	v_add_u32_e32 v152, 0x3800, v188
	v_lshlrev_b64 v[8:9], 2, v[152:153]
	v_lshl_add_u64 v[10:11], s[6:7], 0, v[8:9]
	v_lshl_add_u64 v[12:13], s[44:45], 0, v[8:9]
	global_load_dword v128, v[10:11], off
	global_load_dword v129, v[10:11], off offset:512
	global_load_dword v130, v[10:11], off offset:1024
	global_load_dword v131, v[10:11], off offset:1536
	global_load_dword v132, v[10:11], off offset:2048
	global_load_dword v133, v[10:11], off offset:2560
	global_load_dword v134, v[10:11], off offset:3072
	global_load_dword v135, v[10:11], off offset:3584
	global_load_dword v136, v[12:13], off
	global_load_dword v137, v[12:13], off offset:512
	global_load_dword v138, v[12:13], off offset:1024
	global_load_dword v139, v[12:13], off offset:1536
	global_load_dword v140, v[12:13], off offset:2048
	global_load_dword v141, v[12:13], off offset:2560
	global_load_dword v142, v[12:13], off offset:3072
	global_load_dword v143, v[12:13], off offset:3584
	s_waitcnt vmcnt(32)
	v_cvt_pk_bf16_f32 v4, v96, v97
	v_cvt_pk_bf16_f32 v5, v98, v99
	v_cvt_pk_bf16_f32 v6, v100, v101
	v_cvt_pk_bf16_f32 v7, v102, v103
	ds_write_b128 v2, v[4:7] offset:5120
	v_cvt_pk_bf16_f32 v144, v104, v105
	v_cvt_pk_bf16_f32 v145, v106, v107
	v_cvt_pk_bf16_f32 v146, v108, v109
	v_cvt_pk_bf16_f32 v147, v110, v111
	ds_write_b128 v2, v[144:147] offset:13312
	s_waitcnt vmcnt(16)
	v_cvt_pk_bf16_f32 v4, v112, v113
	v_cvt_pk_bf16_f32 v5, v114, v115
	v_cvt_pk_bf16_f32 v6, v116, v117
	v_cvt_pk_bf16_f32 v7, v118, v119
	ds_write_b128 v2, v[4:7] offset:6144
	v_cvt_pk_bf16_f32 v144, v120, v121
	v_cvt_pk_bf16_f32 v145, v122, v123
	v_cvt_pk_bf16_f32 v146, v124, v125
	v_cvt_pk_bf16_f32 v147, v126, v127
	ds_write_b128 v2, v[144:147] offset:14336
	s_waitcnt vmcnt(0)
	v_cvt_pk_bf16_f32 v4, v128, v129
	v_cvt_pk_bf16_f32 v5, v130, v131
	v_cvt_pk_bf16_f32 v6, v132, v133
	v_cvt_pk_bf16_f32 v7, v134, v135
	ds_write_b128 v2, v[4:7] offset:7168
	v_cvt_pk_bf16_f32 v144, v136, v137
	v_cvt_pk_bf16_f32 v145, v138, v139
	v_cvt_pk_bf16_f32 v146, v140, v141
	v_cvt_pk_bf16_f32 v147, v142, v143
	ds_write_b128 v2, v[144:147] offset:15360
	s_lshl_b32 s12, s29, 7
	v_add_u32_e32 v96, s12, v186
	v_ashrrev_i32_e32 v97, 31, v96
	v_readlane_b32 s60, v254, 0
	v_lshlrev_b64 v[4:5], 2, v[96:97]
	v_readlane_b32 s61, v254, 1
	v_readlane_b32 s62, v254, 2
	v_readlane_b32 s63, v254, 3
	v_readlane_b32 s64, v254, 4
	v_readlane_b32 s65, v254, 5
	v_readlane_b32 s66, v254, 6
	v_readlane_b32 s67, v254, 7
	v_readlane_b32 s68, v254, 8
	v_readlane_b32 s69, v254, 9
	v_readlane_b32 s70, v254, 10
	v_readlane_b32 s71, v254, 11
	v_readlane_b32 s72, v254, 12
	v_readlane_b32 s73, v254, 13
	v_readlane_b32 s74, v254, 14
	v_readlane_b32 s75, v254, 15
	s_waitcnt lgkmcnt(0)
	s_mov_b32 s6, 0xc1a00000
	s_nop 0
	s_nop 0
	v_readlane_b32 s60, v254, 34
	v_readlane_b32 s64, v254, 38
	v_readlane_b32 s65, v254, 39
	v_readlane_b32 s62, v254, 36
	v_readlane_b32 s63, v254, 37
	s_nop 0
	s_nop 0
	s_nop 0
	s_nop 0
	v_readlane_b32 s61, v254, 35
	s_nop 0
	ds_read_b128 v[32:35], v187
	ds_read_b128 v[36:39], v187 offset:1024
	ds_read_b128 v[40:43], v187 offset:2048
	ds_read_b128 v[44:47], v187 offset:3072
	ds_read_b128 v[48:51], v187 offset:4096
	ds_read_b128 v[52:55], v187 offset:5120
	ds_read_b128 v[56:59], v187 offset:6144
	ds_read_b128 v[60:63], v187 offset:7168
	ds_read_b128 v[64:67], v187 offset:8192
	ds_read_b128 v[68:71], v187 offset:9216
	ds_read_b128 v[72:75], v187 offset:10240
	ds_read_b128 v[76:79], v187 offset:11264
	ds_read_b128 v[80:83], v187 offset:12288
	ds_read_b128 v[84:87], v187 offset:13312
	ds_read_b128 v[88:91], v187 offset:14336
	ds_read_b128 v[92:95], v187 offset:15360
	v_readlane_b32 s66, v254, 40
	v_readlane_b32 s67, v254, 41
	v_readlane_b32 s68, v254, 42
	v_readlane_b32 s69, v254, 43
	v_readlane_b32 s70, v254, 44
	v_readlane_b32 s71, v254, 45
	v_readlane_b32 s72, v254, 46
	v_readlane_b32 s73, v254, 47
	v_readlane_b32 s74, v254, 48
	v_readlane_b32 s75, v254, 49
	s_waitcnt vmcnt(0)
	v_xor_b32_e32 v2, 0x80000000, v3
	v_cmp_ngt_f32_e32 vcc, s6, v3
	s_and_saveexec_b64 s[6:7], vcc
	s_cbranch_execz .LBB0_581
	v_mul_f32_e32 v2, 0xbfb8aa3b, v3
	v_exp_f32_e32 v16, v2
	s_mov_b32 s20, 0x3f2aaaab
	v_add_f32_e32 v4, 1.0, v16
	v_frexp_mant_f32_e32 v6, v4
	v_cvt_f64_f32_e32 v[2:3], v4
	v_frexp_exp_i32_f64_e32 v2, v[2:3]
	v_cmp_gt_f32_e32 vcc, s20, v6
	v_add_f32_e32 v5, -1.0, v4
	v_sub_f32_e32 v7, v5, v4
	v_subbrev_co_u32_e32 v10, vcc, 0, v2, vcc
	v_sub_u32_e32 v2, 0, v10
	v_sub_f32_e32 v5, v16, v5
	v_add_f32_e32 v7, 1.0, v7
	v_ldexp_f32 v3, v4, v2
	v_add_f32_e32 v5, v5, v7
	v_add_f32_e32 v4, -1.0, v3
	v_add_f32_e32 v6, 1.0, v3
	v_ldexp_f32 v2, v5, v2
	v_add_f32_e32 v5, 1.0, v4
	v_add_f32_e32 v7, -1.0, v6
	v_sub_f32_e32 v5, v3, v5
	v_sub_f32_e32 v3, v3, v7
	v_add_f32_e32 v5, v2, v5
	v_add_f32_e32 v2, v2, v3
	v_add_f32_e32 v11, v6, v2
	v_rcp_f32_e32 v13, v11
	v_sub_f32_e32 v3, v11, v6
	v_sub_f32_e32 v12, v2, v3
	v_add_f32_e32 v3, v4, v5
	v_mul_f32_e32 v15, v3, v13
	v_sub_f32_e32 v2, v3, v4
	v_mul_f32_e32 v4, v11, v15
	v_fma_f32 v6, v15, v11, -v4
	v_fmac_f32_e32 v6, v15, v12
	v_sub_f32_e32 v14, v5, v2
	v_add_f32_e32 v2, v4, v6
	v_sub_f32_e32 v5, v3, v2
	v_pk_add_f32 v[8:9], v[2:3], v[4:5] neg_lo:[0,1] neg_hi:[0,1]
	v_mov_b32_e32 v7, v2
	v_pk_add_f32 v[2:3], v[8:9], v[6:7] neg_lo:[0,1] neg_hi:[0,1]
	s_mov_b32 s20, 0x3f317218
	v_add_f32_e32 v3, v14, v3
	v_add_f32_e32 v2, v2, v3
	v_add_f32_e32 v3, v5, v2
	v_mul_f32_e32 v14, v13, v3
	v_mul_f32_e32 v4, v11, v14
	v_fma_f32 v6, v14, v11, -v4
	v_fmac_f32_e32 v6, v14, v12
	v_sub_f32_e32 v5, v5, v3
	v_add_f32_e32 v11, v2, v5
	v_add_f32_e32 v2, v4, v6
	v_sub_f32_e32 v5, v3, v2
	v_pk_add_f32 v[8:9], v[2:3], v[4:5] neg_lo:[0,1] neg_hi:[0,1]
	v_mov_b32_e32 v7, v2
	v_pk_add_f32 v[2:3], v[8:9], v[6:7] neg_lo:[0,1] neg_hi:[0,1]
	s_nop 0
	v_add_f32_e32 v3, v11, v3
	v_add_f32_e32 v2, v2, v3
	v_add_f32_e32 v3, v15, v14
	v_add_f32_e32 v2, v5, v2
	v_sub_f32_e32 v4, v3, v15
	v_mul_f32_e32 v2, v13, v2
	v_sub_f32_e32 v4, v14, v4
	v_add_f32_e32 v4, v4, v2
	v_add_f32_e32 v6, v3, v4
	v_mul_f32_e32 v7, v6, v6
	v_fmamk_f32 v2, v7, 0x3e9b6dac, v189
	v_fmaak_f32 v159, v7, v2, 0x3f2aaada
	v_cvt_f32_i32_e32 v2, v10
	v_sub_f32_e32 v3, v6, v3
	v_sub_f32_e32 v3, v4, v3
	v_ldexp_f32 v8, v3, 1
	v_mul_f32_e32 v3, v6, v7
	v_ldexp_f32 v5, v6, 1
	v_pk_mul_f32 v[6:7], v[2:3], v[158:159]
	s_nop 0
	v_fma_f32 v4, v2, s20, -v6
	v_fmac_f32_e32 v4, 0xb102e308, v2
	v_pk_add_f32 v[2:3], v[6:7], v[4:5]
	s_mov_b32 s20, 0x7f800000
	v_sub_f32_e32 v5, v3, v5
	v_sub_f32_e32 v5, v7, v5
	v_add_f32_e32 v9, v8, v5
	v_mov_b32_e32 v8, v6
	v_pk_add_f32 v[6:7], v[2:3], v[6:7] neg_lo:[0,1] neg_hi:[0,1]
	v_pk_add_f32 v[10:11], v[2:3], v[8:9]
	v_mov_b32_e32 v5, v2
	v_mov_b32_e32 v7, v11
	v_pk_add_f32 v[12:13], v[4:5], v[6:7] neg_lo:[0,1] neg_hi:[0,1]
	v_pk_add_f32 v[4:5], v[4:5], v[6:7]
	v_mov_b32_e32 v8, v9
	v_pk_add_f32 v[6:7], v[4:5], v[2:3] op_sel:[1,0] op_sel_hi:[0,1] neg_lo:[0,1] neg_hi:[0,1]
	v_pk_add_f32 v[14:15], v[10:11], v[6:7] op_sel_hi:[1,0] neg_lo:[0,1] neg_hi:[0,1]
	v_mov_b32_e32 v10, v11
	v_mov_b32_e32 v11, v5
	v_pk_mov_b32 v[6:7], v[2:3], v[6:7] op_sel:[1,0]
	v_mov_b32_e32 v9, v2
	v_pk_add_f32 v[6:7], v[10:11], v[6:7] neg_lo:[0,1] neg_hi:[0,1]
	v_mov_b32_e32 v14, v12
	v_pk_add_f32 v[2:3], v[8:9], v[6:7] neg_lo:[0,1] neg_hi:[0,1]
	v_mov_b32_e32 v13, v5
	v_pk_add_f32 v[6:7], v[14:15], v[2:3]
	v_cmp_neq_f32_e32 vcc, s20, v16
	v_pk_add_f32 v[8:9], v[6:7], v[6:7] op_sel:[0,1] op_sel_hi:[1,0]
	s_mov_b32 s20, 0x33800000
	v_pk_add_f32 v[4:5], v[4:5], v[8:9] op_sel:[1,0] op_sel_hi:[0,1]
	v_mov_b32_e32 v7, v4
	v_pk_add_f32 v[10:11], v[6:7], v[12:13] neg_lo:[0,1] neg_hi:[0,1]
	v_mov_b32_e32 v3, v8
	v_sub_f32_e32 v5, v6, v10
	v_pk_add_f32 v[2:3], v[2:3], v[10:11] neg_lo:[0,1] neg_hi:[0,1]
	v_sub_f32_e32 v5, v12, v5
	v_add_f32_e32 v2, v2, v5
	v_add_f32_e32 v2, v2, v3
	v_add_f32_e32 v2, v4, v2
	v_cndmask_b32_e32 v2, v190, v2, vcc
	v_cmp_ngt_f32_e32 vcc, -1.0, v16
	s_nop 1
	v_cndmask_b32_e32 v2, v191, v2, vcc
	v_cmp_neq_f32_e32 vcc, -1.0, v16
	s_nop 1
	v_cndmask_b32_e32 v2, v192, v2, vcc
	v_cmp_lt_f32_e64 vcc, |v16|, s20
	s_nop 1
	v_cndmask_b32_e32 v2, v2, v16, vcc
